# LN-mix router logits: 12 LDS weight reads kept in flight in spare registers, packed-f32 FMAs with two experts interleaved (320 -> 144 VALU per row), same f32 math
# speedup vs baseline: 1.0102x; 1.0095x over previous
.LBB0_684:
	s_or_b64 exec, exec, s[24:25]
	v_lshlrev_b32_e32 v164, 16, v142
	v_and_b32_e32 v165, 0xffff0000, v142
	v_lshlrev_b32_e32 v162, 16, v144
	v_and_b32_e32 v163, 0xffff0000, v144
	v_pk_mul_f32 v[164:165], v[36:37], v[164:165]
	v_lshlrev_b32_e32 v142, 16, v143
	v_and_b32_e32 v143, 0xffff0000, v143
	v_pk_mul_f32 v[162:163], v[52:53], v[162:163]
	v_pk_fma_f32 v[104:105], v[104:105], s[22:23], v[164:165] op_sel_hi:[1,0,1]
	v_pk_mul_f32 v[142:143], v[38:39], v[142:143]
	v_pk_fma_f32 v[108:109], v[108:109], s[22:23], v[162:163] op_sel_hi:[1,0,1]
	v_and_b32_e32 v163, 0xffff0000, v145
	v_lshlrev_b32_e32 v162, 16, v145
	v_lshlrev_b32_e32 v127, 16, v138
	v_mov_b32_e32 v101, v64
	v_and_b32_e32 v96, 0xffff0000, v140
	v_pk_add_f32 v[164:165], v[104:105], v[104:105] op_sel:[0,1] op_sel_hi:[1,0]
	v_pk_fma_f32 v[106:107], v[106:107], s[22:23], v[142:143] op_sel_hi:[1,0,1]
	v_pk_mul_f32 v[144:145], v[54:55], v[162:163]
	v_pk_mul_f32 v[100:101], v[100:101], v[126:127]
	v_and_b32_e32 v127, 0xffff0000, v138
	v_mul_f32_e32 v163, v77, v96
	v_and_b32_e32 v96, 0xffff0000, v141
	v_pk_add_f32 v[142:143], v[106:107], v[164:165]
	v_lshlrev_b32_e32 v165, 16, v140
	v_lshlrev_b32_e32 v164, 16, v139
	v_and_b32_e32 v138, 0xffff0000, v139
	v_lshlrev_b32_e32 v139, 16, v141
	v_pk_mov_b32 v[140:141], v[66:67], v[78:79] op_sel:[1,0]
	v_pk_fma_f32 v[110:111], v[110:111], s[22:23], v[144:145] op_sel_hi:[1,0,1]
	v_pk_mul_f32 v[138:139], v[140:141], v[138:139]
	v_pk_add_f32 v[140:141], v[106:107], v[142:143] op_sel:[1,0] op_sel_hi:[0,1]
	v_pk_add_f32 v[144:145], v[108:109], v[108:109] op_sel:[0,1] op_sel_hi:[1,0]
	s_waitcnt lgkmcnt(0)
	v_mov_b32_e32 v98, v140
	v_pk_add_f32 v[144:145], v[110:111], v[144:145]
	v_pk_add_f32 v[140:141], v[140:141], s[18:19]
	v_pk_mul_f32 v[98:99], v[98:99], s[0:1]
	v_mov_b32_e32 v149, v65
	v_mul_f32_e32 v96, v79, v96
	v_mov_b32_e32 v141, v99
	v_pk_add_f32 v[98:99], v[110:111], v[144:145] op_sel:[1,0] op_sel_hi:[0,1]
	v_pk_mul_f32 v[148:149], v[148:149], v[126:127]
	v_mov_b32_e32 v99, v96
	v_pk_add_f32 v[98:99], v[140:141], v[98:99]
	v_mov_b32_e32 v140, v100
	v_mov_b32_e32 v141, v148
	v_mov_b32_e32 v148, v101
	v_mov_b32_e32 v166, v66
	v_mov_b32_e32 v167, v76
	v_pk_add_f32 v[100:101], v[140:141], v[148:149]
	v_mul_f32_e32 v97, 0x3fb504f3, v97
	v_pk_mul_f32 v[164:165], v[166:167], v[164:165]
	v_mov_b32_e32 v96, v100
	v_mov_b32_e32 v162, v101
	v_pk_fma_f32 v[102:103], v[102:103], s[22:23], v[164:165] op_sel_hi:[1,0,1]
	v_pk_add_f32 v[96:97], v[96:97], v[162:163]
	v_pk_fma_f32 v[138:139], v[146:147], s[22:23], v[138:139] op_sel_hi:[1,0,1]
	v_pk_add_f32 v[140:141], v[102:103], v[96:97]
	v_mov_b32_e32 v164, v102
	v_pk_add_f32 v[140:141], v[138:139], v[140:141]
	v_mov_b32_e32 v165, v138
	v_pk_add_f32 v[140:141], v[98:99], v[140:141]
	v_ashrrev_i32_e32 v115, 31, v114
	v_add_f32_e32 v96, v140, v141
	ds_bpermute_b32 v98, v150, v96
	s_waitcnt lgkmcnt(0)
	v_add_f32_e32 v96, v96, v98
	ds_bpermute_b32 v98, v151, v96
	s_waitcnt lgkmcnt(0)
	v_add_f32_e32 v96, v96, v98
	ds_bpermute_b32 v98, v152, v96
	s_waitcnt lgkmcnt(0)
	v_add_f32_e32 v96, v96, v98
	ds_bpermute_b32 v98, v153, v96
	s_waitcnt lgkmcnt(0)
	v_add_f32_e32 v96, v96, v98
	ds_bpermute_b32 v98, v154, v96
	s_waitcnt lgkmcnt(0)
	v_add_f32_e32 v96, v96, v98
	ds_bpermute_b32 v98, v155, v96
	s_waitcnt lgkmcnt(0)
	v_add_f32_e32 v96, v96, v98
	v_mul_f32_e32 v140, 0x3a800000, v96
	v_pk_add_f32 v[104:105], v[104:105], v[140:141] op_sel_hi:[1,0] neg_lo:[0,1] neg_hi:[0,1]
	v_pk_add_f32 v[106:107], v[106:107], v[140:141] op_sel_hi:[1,0] neg_lo:[0,1] neg_hi:[0,1]
	v_pk_mul_f32 v[142:143], v[104:105], v[104:105]
	v_pk_mul_f32 v[144:145], v[106:107], v[106:107]
	v_add_f32_e32 v102, v142, v143
	v_pk_add_f32 v[108:109], v[108:109], v[140:141] op_sel_hi:[1,0] neg_lo:[0,1] neg_hi:[0,1]
	v_add_f32_e32 v102, v144, v102
	v_pk_mul_f32 v[148:149], v[108:109], v[108:109]
	v_add_f32_e32 v102, v145, v102
	v_pk_add_f32 v[110:111], v[110:111], v[140:141] op_sel_hi:[1,0] neg_lo:[0,1] neg_hi:[0,1]
	v_add_f32_e32 v102, v148, v102
	v_pk_mul_f32 v[162:163], v[110:111], v[110:111]
	v_add_f32_e32 v102, v149, v102
	v_pk_add_f32 v[146:147], v[100:101], v[140:141] op_sel_hi:[1,0] neg_lo:[0,1] neg_hi:[0,1]
	v_add_f32_e32 v102, v162, v102
	v_pk_mul_f32 v[100:101], v[146:147], v[146:147]
	v_add_f32_e32 v102, v163, v102
	v_pk_add_f32 v[164:165], v[164:165], v[140:141] op_sel_hi:[1,0] neg_lo:[0,1] neg_hi:[0,1]
	v_add_f32_e32 v100, v100, v102
	v_pk_mul_f32 v[166:167], v[164:165], v[164:165]
	v_mov_b32_e32 v96, v103
	v_add_f32_e32 v100, v101, v100
	v_pk_add_f32 v[168:169], v[96:97], v[140:141] op_sel_hi:[1,0] neg_lo:[0,1] neg_hi:[0,1]
	v_add_f32_e32 v100, v166, v100
	v_pk_mul_f32 v[96:97], v[168:169], v[168:169]
	v_mov_b32_e32 v98, v139
	v_add_f32_e32 v100, v167, v100
	v_pk_add_f32 v[138:139], v[98:99], v[140:141] op_sel_hi:[1,0] neg_lo:[0,1] neg_hi:[0,1]
	v_add_f32_e32 v96, v96, v100
	v_pk_mul_f32 v[98:99], v[138:139], v[138:139]
	v_add_f32_e32 v96, v97, v96
	v_add_f32_e32 v96, v98, v96
	v_add_f32_e32 v96, v99, v96
	ds_bpermute_b32 v97, v150, v96
	v_pk_add_f32 v[102:103], v[34:35], 1.0 op_sel_hi:[1,0]
	v_pk_add_f32 v[144:145], v[40:41], 1.0 op_sel_hi:[1,0]
	v_pk_add_f32 v[148:149], v[42:43], 1.0 op_sel_hi:[1,0]
	v_pk_add_f32 v[162:163], v[56:57], 1.0 op_sel_hi:[1,0]
	s_waitcnt lgkmcnt(0)
	v_add_f32_e32 v96, v96, v97
	ds_bpermute_b32 v97, v151, v96
	v_pk_add_f32 v[166:167], v[58:59], 1.0 op_sel_hi:[1,0]
	s_waitcnt lgkmcnt(0)
	v_add_f32_e32 v96, v96, v97
	ds_bpermute_b32 v97, v152, v96
	s_waitcnt lgkmcnt(0)
	v_add_f32_e32 v96, v96, v97
	ds_bpermute_b32 v97, v153, v96
	s_waitcnt lgkmcnt(0)
	v_add_f32_e32 v98, v96, v97
	ds_bpermute_b32 v99, v154, v98
	v_lshlrev_b64 v[96:97], 12, v[114:115]
	v_lshl_add_u64 v[140:141], v[122:123], 0, v[96:97]
	v_pk_add_f32 v[96:97], v[32:33], 1.0 op_sel_hi:[1,0]
	s_waitcnt lgkmcnt(0)
	v_add_f32_e32 v100, v98, v99
	ds_bpermute_b32 v101, v155, v100
	v_lshlrev_b64 v[98:99], 11, v[114:115]
	v_lshl_add_u64 v[142:143], v[124:125], 0, v[98:99]
	s_waitcnt lgkmcnt(0)
	v_add_f32_e32 v98, v100, v101
	v_fmamk_f32 v98, v98, 0x3a800000, v159
	v_mul_f32_e32 v99, 0x4b800000, v98
	v_cmp_gt_f32_e32 vcc, s19, v98
	s_nop 1
	v_cndmask_b32_e32 v98, v98, v99, vcc
	v_rsq_f32_e32 v98, v98
	s_nop 0
	v_mul_f32_e32 v99, 0x45800000, v98
	v_cndmask_b32_e32 v170, v98, v99, vcc
	v_pk_mul_f32 v[98:99], v[104:105], v[170:171] op_sel_hi:[1,0]
	v_pk_mul_f32 v[100:101], v[106:107], v[170:171] op_sel_hi:[1,0]
	v_pk_fma_f32 v[98:99], v[28:29], v[98:99], v[24:25]
	v_pk_fma_f32 v[100:101], v[30:31], v[100:101], v[26:27]
	global_store_dwordx4 v[140:141], v[98:101], off sc1 nt
	s_nop 1
	v_pk_fma_f32 v[98:99], v[96:97], v[98:99], v[44:45]
	v_pk_fma_f32 v[96:97], v[102:103], v[100:101], v[46:47]
	v_cvt_pk_bf16_f32 v100, v98, v99
	v_cvt_pk_bf16_f32 v101, v96, v97
	global_store_dwordx2 v[142:143], v[100:101], off
	v_pk_mul_f32 v[100:101], v[108:109], v[170:171] op_sel_hi:[1,0]
	s_nop 0
	v_pk_fma_f32 v[102:103], v[20:21], v[100:101], v[16:17]
	v_pk_mul_f32 v[100:101], v[110:111], v[170:171] op_sel_hi:[1,0]
	v_pk_mul_f32 v[110:111], v[138:139], v[170:171] op_sel_hi:[1,0]
	v_pk_fma_f32 v[104:105], v[22:23], v[100:101], v[18:19]
	global_store_dwordx4 v[140:141], v[102:105], off offset:1024 sc1 nt
	v_pk_fma_f32 v[100:101], v[148:149], v[104:105], v[50:51]
	v_pk_fma_f32 v[110:111], v[6:7], v[110:111], v[2:3]
	v_pk_fma_f32 v[102:103], v[144:145], v[102:103], v[48:49]
	v_cvt_pk_bf16_f32 v105, v100, v101
	v_cvt_pk_bf16_f32 v104, v102, v103
	global_store_dwordx2 v[142:143], v[104:105], off offset:512
	v_pk_mul_f32 v[104:105], v[146:147], v[170:171] op_sel_hi:[1,0]
	v_pk_add_f32 v[138:139], v[68:69], 1.0 op_sel_hi:[1,0]
	v_pk_fma_f32 v[106:107], v[12:13], v[104:105], v[8:9]
	v_pk_mul_f32 v[104:105], v[164:165], v[170:171] op_sel_hi:[1,0]
	s_nop 0
	v_pk_fma_f32 v[108:109], v[14:15], v[104:105], v[10:11]
	global_store_dwordx4 v[140:141], v[106:109], off offset:2048 sc1 nt
	v_pk_fma_f32 v[104:105], v[166:167], v[108:109], v[62:63]
	s_nop 0
	v_pk_fma_f32 v[106:107], v[162:163], v[106:107], v[60:61]
	v_cvt_pk_bf16_f32 v109, v104, v105
	v_cvt_pk_bf16_f32 v108, v106, v107
	global_store_dwordx2 v[142:143], v[108:109], off offset:1024
	v_pk_mul_f32 v[108:109], v[168:169], v[170:171] op_sel_hi:[1,0]
	s_nop 0
	v_pk_fma_f32 v[108:109], v[4:5], v[108:109], v[0:1]
	global_store_dwordx4 v[140:141], v[108:111], off offset:3072 sc1 nt
	s_nop 1
	v_pk_fma_f32 v[108:109], v[138:139], v[108:109], v[72:73]
	v_pk_add_f32 v[138:139], v[70:71], 1.0 op_sel_hi:[1,0]
	v_cvt_pk_bf16_f32 v144, v108, v109
	v_pk_fma_f32 v[110:111], v[138:139], v[110:111], v[74:75]
	v_cvt_pk_bf16_f32 v145, v110, v111
	global_store_dwordx2 v[142:143], v[144:145], off offset:1536
	ds_read_b128 v[216:219], v156
	ds_read_b128 v[220:223], v156 offset:4096
	ds_read_b128 v[224:227], v156 offset:1024
	ds_read_b128 v[228:231], v156 offset:5120
	ds_read_b128 v[232:235], v156 offset:2048
	ds_read_b128 v[236:239], v156 offset:6144
	ds_read_b128 v[240:243], v156 offset:3072
	ds_read_b128 v[244:247], v156 offset:7168
	ds_read_b128 v[248:251], v156 offset:8192
	ds_read_b128 v[192:195], v156 offset:12288
	ds_read_b128 v[196:199], v156 offset:9216
	ds_read_b128 v[200:203], v156 offset:13312
	s_waitcnt lgkmcnt(10)
	v_pk_mul_f32 v[204:205], v[98:99], v[216:217]
	v_pk_mul_f32 v[206:207], v[98:99], v[220:221]
	v_pk_fma_f32 v[204:205], v[96:97], v[218:219], v[204:205]
	v_pk_fma_f32 v[206:207], v[96:97], v[222:223], v[206:207]
	ds_read_b128 v[216:219], v156 offset:10240
	ds_read_b128 v[220:223], v156 offset:14336
	s_waitcnt lgkmcnt(10)
	v_pk_fma_f32 v[204:205], v[102:103], v[224:225], v[204:205]
	v_pk_fma_f32 v[206:207], v[102:103], v[228:229], v[206:207]
	v_pk_fma_f32 v[204:205], v[100:101], v[226:227], v[204:205]
	v_pk_fma_f32 v[206:207], v[100:101], v[230:231], v[206:207]
	ds_read_b128 v[224:227], v156 offset:11264
	ds_read_b128 v[228:231], v156 offset:15360
	s_waitcnt lgkmcnt(10)
	v_pk_fma_f32 v[204:205], v[106:107], v[232:233], v[204:205]
	v_pk_fma_f32 v[206:207], v[106:107], v[236:237], v[206:207]
	v_pk_fma_f32 v[204:205], v[104:105], v[234:235], v[204:205]
	v_pk_fma_f32 v[206:207], v[104:105], v[238:239], v[206:207]
	ds_read_b128 v[232:235], v156 offset:16384
	ds_read_b128 v[236:239], v156 offset:20480
	s_waitcnt lgkmcnt(10)
	v_pk_fma_f32 v[204:205], v[108:109], v[240:241], v[204:205]
	v_pk_fma_f32 v[206:207], v[108:109], v[244:245], v[206:207]
	v_pk_fma_f32 v[204:205], v[110:111], v[242:243], v[204:205]
	v_pk_fma_f32 v[206:207], v[110:111], v[246:247], v[206:207]
	ds_read_b128 v[240:243], v156 offset:17408
	ds_read_b128 v[244:247], v156 offset:21504
	v_add_f32_e32 v115, v204, v205
	v_add_f32_e32 v127, v206, v207
	s_waitcnt lgkmcnt(10)
	v_pk_mul_f32 v[208:209], v[98:99], v[248:249]
	v_pk_mul_f32 v[210:211], v[98:99], v[192:193]
	v_pk_fma_f32 v[208:209], v[96:97], v[250:251], v[208:209]
	v_pk_fma_f32 v[210:211], v[96:97], v[194:195], v[210:211]
	ds_read_b128 v[248:251], v156 offset:18432
	ds_read_b128 v[192:195], v156 offset:22528
	s_waitcnt lgkmcnt(10)
	v_pk_fma_f32 v[208:209], v[102:103], v[196:197], v[208:209]
	v_pk_fma_f32 v[210:211], v[102:103], v[200:201], v[210:211]
	v_pk_fma_f32 v[208:209], v[100:101], v[198:199], v[208:209]
	v_pk_fma_f32 v[210:211], v[100:101], v[202:203], v[210:211]
	ds_read_b128 v[196:199], v156 offset:19456
	ds_read_b128 v[200:203], v156 offset:23552
	s_waitcnt lgkmcnt(10)
	v_pk_fma_f32 v[208:209], v[106:107], v[216:217], v[208:209]
	v_pk_fma_f32 v[210:211], v[106:107], v[220:221], v[210:211]
	v_pk_fma_f32 v[208:209], v[104:105], v[218:219], v[208:209]
	v_pk_fma_f32 v[210:211], v[104:105], v[222:223], v[210:211]
	ds_read_b128 v[216:219], v156 offset:24576
	ds_read_b128 v[220:223], v156 offset:28672
	s_waitcnt lgkmcnt(10)
	v_pk_fma_f32 v[208:209], v[108:109], v[224:225], v[208:209]
	v_pk_fma_f32 v[210:211], v[108:109], v[228:229], v[210:211]
	v_pk_fma_f32 v[208:209], v[110:111], v[226:227], v[208:209]
	v_pk_fma_f32 v[210:211], v[110:111], v[230:231], v[210:211]
	ds_read_b128 v[224:227], v156 offset:25600
	ds_read_b128 v[228:231], v156 offset:29696
	v_add_f32_e32 v129, v208, v209
	v_add_f32_e32 v138, v210, v211
	s_waitcnt lgkmcnt(10)
	v_pk_mul_f32 v[204:205], v[98:99], v[232:233]
	v_pk_mul_f32 v[206:207], v[98:99], v[236:237]
	v_pk_fma_f32 v[204:205], v[96:97], v[234:235], v[204:205]
	v_pk_fma_f32 v[206:207], v[96:97], v[238:239], v[206:207]
	ds_read_b128 v[232:235], v156 offset:26624
	ds_read_b128 v[236:239], v156 offset:30720
	s_waitcnt lgkmcnt(10)
	v_pk_fma_f32 v[204:205], v[102:103], v[240:241], v[204:205]
	v_pk_fma_f32 v[206:207], v[102:103], v[244:245], v[206:207]
	v_pk_fma_f32 v[204:205], v[100:101], v[242:243], v[204:205]
	v_pk_fma_f32 v[206:207], v[100:101], v[246:247], v[206:207]
	ds_read_b128 v[240:243], v156 offset:27648
	ds_read_b128 v[244:247], v156 offset:31744
	s_waitcnt lgkmcnt(10)
	v_pk_fma_f32 v[204:205], v[106:107], v[248:249], v[204:205]
	v_pk_fma_f32 v[206:207], v[106:107], v[192:193], v[206:207]
	v_pk_fma_f32 v[204:205], v[104:105], v[250:251], v[204:205]
	v_pk_fma_f32 v[206:207], v[104:105], v[194:195], v[206:207]
	ds_read_b128 v[248:251], v156 offset:32768
	ds_read_b128 v[192:195], v156 offset:36864
	s_waitcnt lgkmcnt(10)
	v_pk_fma_f32 v[204:205], v[108:109], v[196:197], v[204:205]
	v_pk_fma_f32 v[206:207], v[108:109], v[200:201], v[206:207]
	v_pk_fma_f32 v[204:205], v[110:111], v[198:199], v[204:205]
	v_pk_fma_f32 v[206:207], v[110:111], v[202:203], v[206:207]
	ds_read_b128 v[196:199], v156 offset:33792
	ds_read_b128 v[200:203], v156 offset:37888
	v_add_f32_e32 v139, v204, v205
	v_add_f32_e32 v148, v206, v207
	s_waitcnt lgkmcnt(10)
	v_pk_mul_f32 v[208:209], v[98:99], v[216:217]
	v_pk_mul_f32 v[210:211], v[98:99], v[220:221]
	v_pk_fma_f32 v[208:209], v[96:97], v[218:219], v[208:209]
	v_pk_fma_f32 v[210:211], v[96:97], v[222:223], v[210:211]
	ds_read_b128 v[216:219], v156 offset:34816
	ds_read_b128 v[220:223], v156 offset:38912
	s_waitcnt lgkmcnt(10)
	v_pk_fma_f32 v[208:209], v[102:103], v[224:225], v[208:209]
	v_pk_fma_f32 v[210:211], v[102:103], v[228:229], v[210:211]
	v_pk_fma_f32 v[208:209], v[100:101], v[226:227], v[208:209]
	v_pk_fma_f32 v[210:211], v[100:101], v[230:231], v[210:211]
	ds_read_b128 v[224:227], v156 offset:35840
	ds_read_b128 v[228:231], v156 offset:39936
	s_waitcnt lgkmcnt(10)
	v_pk_fma_f32 v[208:209], v[106:107], v[232:233], v[208:209]
	v_pk_fma_f32 v[210:211], v[106:107], v[236:237], v[210:211]
	v_pk_fma_f32 v[208:209], v[104:105], v[234:235], v[208:209]
	v_pk_fma_f32 v[210:211], v[104:105], v[238:239], v[210:211]
	ds_read_b128 v[232:235], v156 offset:40960
	ds_read_b128 v[236:239], v156 offset:45056
	s_waitcnt lgkmcnt(10)
	v_pk_fma_f32 v[208:209], v[108:109], v[240:241], v[208:209]
	v_pk_fma_f32 v[210:211], v[108:109], v[244:245], v[210:211]
	v_pk_fma_f32 v[208:209], v[110:111], v[242:243], v[208:209]
	v_pk_fma_f32 v[210:211], v[110:111], v[246:247], v[210:211]
	ds_read_b128 v[240:243], v156 offset:41984
	ds_read_b128 v[244:247], v156 offset:46080
	v_add_f32_e32 v149, v208, v209
	v_add_f32_e32 v161, v210, v211
	s_waitcnt lgkmcnt(10)
	v_pk_mul_f32 v[204:205], v[98:99], v[248:249]
	v_pk_mul_f32 v[206:207], v[98:99], v[192:193]
	v_pk_fma_f32 v[204:205], v[96:97], v[250:251], v[204:205]
	v_pk_fma_f32 v[206:207], v[96:97], v[194:195], v[206:207]
	ds_read_b128 v[248:251], v156 offset:43008
	ds_read_b128 v[192:195], v156 offset:47104
	s_waitcnt lgkmcnt(10)
	v_pk_fma_f32 v[204:205], v[102:103], v[196:197], v[204:205]
	v_pk_fma_f32 v[206:207], v[102:103], v[200:201], v[206:207]
	v_pk_fma_f32 v[204:205], v[100:101], v[198:199], v[204:205]
	v_pk_fma_f32 v[206:207], v[100:101], v[202:203], v[206:207]
	ds_read_b128 v[196:199], v156 offset:44032
	ds_read_b128 v[200:203], v156 offset:48128
	s_waitcnt lgkmcnt(10)
	v_pk_fma_f32 v[204:205], v[106:107], v[216:217], v[204:205]
	v_pk_fma_f32 v[206:207], v[106:107], v[220:221], v[206:207]
	v_pk_fma_f32 v[204:205], v[104:105], v[218:219], v[204:205]
	v_pk_fma_f32 v[206:207], v[104:105], v[222:223], v[206:207]
	ds_read_b128 v[216:219], v156 offset:49152
	ds_read_b128 v[220:223], v156 offset:53248
	s_waitcnt lgkmcnt(10)
	v_pk_fma_f32 v[204:205], v[108:109], v[224:225], v[204:205]
	v_pk_fma_f32 v[206:207], v[108:109], v[228:229], v[206:207]
	v_pk_fma_f32 v[204:205], v[110:111], v[226:227], v[204:205]
	v_pk_fma_f32 v[206:207], v[110:111], v[230:231], v[206:207]
	ds_read_b128 v[224:227], v156 offset:50176
	ds_read_b128 v[228:231], v156 offset:54272
	v_add_f32_e32 v170, v204, v205
	v_add_f32_e32 v171, v206, v207
	s_waitcnt lgkmcnt(10)
	v_pk_mul_f32 v[208:209], v[98:99], v[232:233]
	v_pk_mul_f32 v[210:211], v[98:99], v[236:237]
	v_pk_fma_f32 v[208:209], v[96:97], v[234:235], v[208:209]
	v_pk_fma_f32 v[210:211], v[96:97], v[238:239], v[210:211]
	ds_read_b128 v[232:235], v156 offset:51200
	ds_read_b128 v[236:239], v156 offset:55296
	s_waitcnt lgkmcnt(10)
	v_pk_fma_f32 v[208:209], v[102:103], v[240:241], v[208:209]
	v_pk_fma_f32 v[210:211], v[102:103], v[244:245], v[210:211]
	v_pk_fma_f32 v[208:209], v[100:101], v[242:243], v[208:209]
	v_pk_fma_f32 v[210:211], v[100:101], v[246:247], v[210:211]
	ds_read_b128 v[240:243], v156 offset:52224
	ds_read_b128 v[244:247], v156 offset:56320
	s_waitcnt lgkmcnt(10)
	v_pk_fma_f32 v[208:209], v[106:107], v[248:249], v[208:209]
	v_pk_fma_f32 v[210:211], v[106:107], v[192:193], v[210:211]
	v_pk_fma_f32 v[208:209], v[104:105], v[250:251], v[208:209]
	v_pk_fma_f32 v[210:211], v[104:105], v[194:195], v[210:211]
	ds_read_b128 v[248:251], v156 offset:57344
	ds_read_b128 v[192:195], v156 offset:61440
	s_waitcnt lgkmcnt(10)
	v_pk_fma_f32 v[208:209], v[108:109], v[196:197], v[208:209]
	v_pk_fma_f32 v[210:211], v[108:109], v[200:201], v[210:211]
	v_pk_fma_f32 v[208:209], v[110:111], v[198:199], v[208:209]
	v_pk_fma_f32 v[210:211], v[110:111], v[202:203], v[210:211]
	ds_read_b128 v[196:199], v156 offset:58368
	ds_read_b128 v[200:203], v156 offset:62464
	v_add_f32_e32 v172, v208, v209
	v_add_f32_e32 v173, v210, v211
	s_waitcnt lgkmcnt(10)
	v_pk_mul_f32 v[204:205], v[98:99], v[216:217]
	v_pk_mul_f32 v[206:207], v[98:99], v[220:221]
	v_pk_fma_f32 v[204:205], v[96:97], v[218:219], v[204:205]
	v_pk_fma_f32 v[206:207], v[96:97], v[222:223], v[206:207]
	ds_read_b128 v[216:219], v156 offset:59392
	ds_read_b128 v[220:223], v156 offset:63488
	s_waitcnt lgkmcnt(10)
	v_pk_fma_f32 v[204:205], v[102:103], v[224:225], v[204:205]
	v_pk_fma_f32 v[206:207], v[102:103], v[228:229], v[206:207]
	v_pk_fma_f32 v[204:205], v[100:101], v[226:227], v[204:205]
	v_pk_fma_f32 v[206:207], v[100:101], v[230:231], v[206:207]
	ds_read_b128 v[224:227], v156 offset:60416
	ds_read_b128 v[228:231], v156 offset:64512
	s_waitcnt lgkmcnt(10)
	v_pk_fma_f32 v[204:205], v[106:107], v[232:233], v[204:205]
	v_pk_fma_f32 v[206:207], v[106:107], v[236:237], v[206:207]
	v_pk_fma_f32 v[204:205], v[104:105], v[234:235], v[204:205]
	v_pk_fma_f32 v[206:207], v[104:105], v[238:239], v[206:207]
	s_waitcnt lgkmcnt(8)
	v_pk_fma_f32 v[204:205], v[108:109], v[240:241], v[204:205]
	v_pk_fma_f32 v[206:207], v[108:109], v[244:245], v[206:207]
	v_pk_fma_f32 v[204:205], v[110:111], v[242:243], v[204:205]
	v_pk_fma_f32 v[206:207], v[110:111], v[246:247], v[206:207]
	v_add_f32_e32 v174, v204, v205
	v_add_f32_e32 v175, v206, v207
	s_waitcnt lgkmcnt(6)
	v_pk_mul_f32 v[208:209], v[98:99], v[248:249]
	v_pk_mul_f32 v[210:211], v[98:99], v[192:193]
	v_pk_fma_f32 v[208:209], v[96:97], v[250:251], v[208:209]
	v_pk_fma_f32 v[210:211], v[96:97], v[194:195], v[210:211]
	s_waitcnt lgkmcnt(4)
	v_pk_fma_f32 v[208:209], v[102:103], v[196:197], v[208:209]
	v_pk_fma_f32 v[210:211], v[102:103], v[200:201], v[210:211]
	v_pk_fma_f32 v[208:209], v[100:101], v[198:199], v[208:209]
	v_pk_fma_f32 v[210:211], v[100:101], v[202:203], v[210:211]
	s_waitcnt lgkmcnt(2)
	v_pk_fma_f32 v[208:209], v[106:107], v[216:217], v[208:209]
	v_pk_fma_f32 v[210:211], v[106:107], v[220:221], v[210:211]
	v_pk_fma_f32 v[208:209], v[104:105], v[218:219], v[208:209]
	v_pk_fma_f32 v[210:211], v[104:105], v[222:223], v[210:211]
	s_waitcnt lgkmcnt(0)
	v_pk_fma_f32 v[208:209], v[108:109], v[224:225], v[208:209]
	v_pk_fma_f32 v[210:211], v[108:109], v[228:229], v[210:211]
	v_pk_fma_f32 v[208:209], v[110:111], v[226:227], v[208:209]
	v_pk_fma_f32 v[210:211], v[110:111], v[230:231], v[210:211]
	v_add_f32_e32 v176, v208, v209
	v_add_f32_e32 v96, v210, v211
	v_cndmask_b32_e64 v97, v115, v170, s[6:7]
	ds_bpermute_b32 v97, v150, v97
	v_cndmask_b32_e64 v99, v127, v171, s[6:7]
	ds_bpermute_b32 v99, v150, v99
	v_cndmask_b32_e64 v100, v129, v172, s[6:7]
	ds_bpermute_b32 v100, v150, v100
	v_cndmask_b32_e64 v98, v170, v115, s[6:7]
	s_waitcnt lgkmcnt(2)
	v_add_f32_e32 v97, v98, v97
	v_cndmask_b32_e64 v98, v171, v127, s[6:7]
	s_waitcnt lgkmcnt(1)
	v_add_f32_e32 v98, v98, v99
	v_cndmask_b32_e64 v99, v172, v129, s[6:7]
	s_waitcnt lgkmcnt(0)
	v_add_f32_e32 v99, v99, v100
	v_cndmask_b32_e64 v100, v138, v173, s[6:7]
	ds_bpermute_b32 v100, v150, v100
	v_cndmask_b32_e64 v102, v139, v174, s[6:7]
	ds_bpermute_b32 v102, v150, v102
	v_cndmask_b32_e64 v103, v148, v175, s[6:7]
	ds_bpermute_b32 v103, v150, v103
	v_cndmask_b32_e64 v101, v173, v138, s[6:7]
	s_waitcnt lgkmcnt(2)
	v_add_f32_e32 v100, v101, v100
	v_cndmask_b32_e64 v101, v174, v139, s[6:7]
	s_waitcnt lgkmcnt(1)
	v_add_f32_e32 v101, v101, v102
	v_cndmask_b32_e64 v102, v175, v148, s[6:7]
	s_waitcnt lgkmcnt(0)
	v_add_f32_e32 v102, v102, v103
	v_cndmask_b32_e64 v103, v149, v176, s[6:7]
	v_cndmask_b32_e64 v105, v161, v96, s[6:7]
	ds_bpermute_b32 v103, v150, v103
	ds_bpermute_b32 v105, v150, v105
	v_cndmask_b32_e64 v104, v176, v149, s[6:7]
	v_cndmask_b32_e64 v96, v96, v161, s[6:7]
	v_cndmask_b32_e64 v106, v97, v101, s[8:9]
	s_waitcnt lgkmcnt(1)
	v_add_f32_e32 v103, v104, v103
	s_waitcnt lgkmcnt(0)
	v_add_f32_e32 v96, v96, v105
	v_cndmask_b32_e64 v97, v101, v97, s[8:9]
	v_cndmask_b32_e64 v101, v98, v102, s[8:9]
	v_cndmask_b32_e64 v98, v102, v98, s[8:9]
	v_cndmask_b32_e64 v102, v99, v103, s[8:9]
	v_cndmask_b32_e64 v104, v100, v96, s[8:9]
	ds_bpermute_b32 v106, v151, v106
	ds_bpermute_b32 v101, v151, v101
	ds_bpermute_b32 v102, v151, v102
	ds_bpermute_b32 v104, v151, v104
	v_cndmask_b32_e64 v99, v103, v99, s[8:9]
	v_cndmask_b32_e64 v96, v96, v100, s[8:9]
	s_waitcnt lgkmcnt(3)
	v_add_f32_e32 v97, v97, v106
	s_waitcnt lgkmcnt(2)
	v_add_f32_e32 v98, v98, v101
	s_waitcnt lgkmcnt(1)
	v_add_f32_e32 v99, v99, v102
	s_waitcnt lgkmcnt(0)
	v_add_f32_e32 v96, v96, v104
	v_cndmask_b32_e64 v100, v97, v99, s[10:11]
	v_cndmask_b32_e64 v101, v98, v96, s[10:11]
	ds_bpermute_b32 v100, v152, v100
	ds_bpermute_b32 v101, v152, v101
	v_cndmask_b32_e64 v97, v99, v97, s[10:11]
	v_cndmask_b32_e64 v96, v96, v98, s[10:11]
	s_waitcnt lgkmcnt(1)
	v_add_f32_e32 v97, v97, v100
	s_waitcnt lgkmcnt(0)
	v_add_f32_e32 v96, v96, v101
	v_cndmask_b32_e64 v98, v97, v96, s[12:13]
	ds_bpermute_b32 v98, v153, v98
	v_cndmask_b32_e64 v96, v96, v97, s[12:13]
	s_waitcnt lgkmcnt(0)
	v_add_f32_e32 v96, v96, v98
	ds_bpermute_b32 v97, v154, v96
	s_waitcnt lgkmcnt(0)
	v_add_f32_e32 v96, v96, v97
	ds_bpermute_b32 v97, v155, v96
	s_waitcnt lgkmcnt(0)
	v_add_f32_e32 v96, v96, v97
	ds_bpermute_b32 v97, v153, v96
	s_waitcnt lgkmcnt(0)
	v_max_f32_e32 v97, v97, v97
	v_max_f32_e32 v97, v96, v97
	ds_bpermute_b32 v98, v152, v97
	s_waitcnt lgkmcnt(0)
	v_max_f32_e32 v98, v98, v98
	v_max_f32_e32 v97, v97, v98
	ds_bpermute_b32 v98, v151, v97
	s_waitcnt lgkmcnt(0)
	v_max_f32_e32 v98, v98, v98
	v_max_f32_e32 v97, v97, v98
	ds_bpermute_b32 v98, v150, v97
	s_waitcnt lgkmcnt(0)
	v_max_f32_e32 v98, v98, v98
	v_max_f32_e32 v97, v97, v98
	v_sub_f32_e32 v96, v96, v97
	v_mul_f32_e32 v97, 0x3fb8aa3b, v96
	v_fma_f32 v98, v96, s23, -v97
	v_rndne_f32_e32 v99, v97
	v_fmac_f32_e32 v98, 0x32a5705f, v96
	v_sub_f32_e32 v97, v97, v99
	v_add_f32_e32 v97, v97, v98
	v_exp_f32_e32 v97, v97
	v_cvt_i32_f32_e32 v98, v99
	v_cmp_ngt_f32_e32 vcc, s26, v96
	v_ldexp_f32 v97, v97, v98
	s_nop 0
	v_cndmask_b32_e32 v97, 0, v97, vcc
	v_cmp_nlt_f32_e32 vcc, s27, v96
	s_nop 1
	v_cndmask_b32_e32 v96, v160, v97, vcc
	ds_bpermute_b32 v97, v153, v96
	s_waitcnt lgkmcnt(0)
	v_add_f32_e32 v97, v96, v97
	ds_bpermute_b32 v98, v152, v97
	s_waitcnt lgkmcnt(0)
	v_add_f32_e32 v97, v97, v98
	ds_bpermute_b32 v98, v151, v97
	s_waitcnt lgkmcnt(0)
	v_add_f32_e32 v97, v97, v98
	ds_bpermute_b32 v98, v150, v97
	s_and_saveexec_b64 s[24:25], s[14:15]
	s_cbranch_execz .LBB0_679
	s_waitcnt lgkmcnt(0)
	v_add_f32_e32 v97, v97, v98
	v_div_scale_f32 v98, s[28:29], v97, v97, v96
	v_rcp_f32_e32 v99, v98
	v_and_b32_e32 v100, 0xfff, v114
	v_fma_f32 v101, -v98, v99, 1.0
	v_fmac_f32_e32 v99, v101, v99
	v_div_scale_f32 v101, vcc, v96, v97, v96
	v_mul_f32_e32 v102, v101, v99
	v_fma_f32 v103, -v98, v102, v101
	v_fmac_f32_e32 v102, v103, v99
	v_fma_f32 v98, -v98, v102, v101
	v_div_fmas_f32 v98, v98, v99, v102
	v_div_fixup_f32 v98, v98, v97, v96
	v_lshl_or_b32 v96, v112, 4, v157
	v_ashrrev_i32_e32 v97, 31, v96
	v_lshlrev_b64 v[96:97], 14, v[96:97]
	v_lshl_add_u64 v[96:97], s[4:5], 0, v[96:97]
	v_lshlrev_b32_e32 v112, 2, v100
	v_lshl_add_u64 v[96:97], v[96:97], 0, v[112:113]
	global_store_dword v[96:97], v98, off
	s_branch .LBB0_679

.LBB0_1399:
	s_or_b64 exec, exec, s[26:27]
	v_lshlrev_b32_e32 v164, 16, v142
	v_and_b32_e32 v165, 0xffff0000, v142
	v_lshlrev_b32_e32 v162, 16, v144
	v_and_b32_e32 v163, 0xffff0000, v144
	v_pk_mul_f32 v[164:165], v[36:37], v[164:165]
	v_lshlrev_b32_e32 v142, 16, v143
	v_and_b32_e32 v143, 0xffff0000, v143
	v_pk_mul_f32 v[162:163], v[52:53], v[162:163]
	v_pk_fma_f32 v[104:105], v[104:105], s[24:25], v[164:165] op_sel_hi:[1,0,1]
	v_pk_mul_f32 v[142:143], v[38:39], v[142:143]
	v_pk_fma_f32 v[108:109], v[108:109], s[24:25], v[162:163] op_sel_hi:[1,0,1]
	v_and_b32_e32 v163, 0xffff0000, v145
	v_lshlrev_b32_e32 v162, 16, v145
	v_lshlrev_b32_e32 v127, 16, v138
	v_mov_b32_e32 v101, v64
	v_and_b32_e32 v96, 0xffff0000, v140
	v_pk_add_f32 v[164:165], v[104:105], v[104:105] op_sel:[0,1] op_sel_hi:[1,0]
	v_pk_fma_f32 v[106:107], v[106:107], s[24:25], v[142:143] op_sel_hi:[1,0,1]
	v_pk_mul_f32 v[144:145], v[54:55], v[162:163]
	v_pk_mul_f32 v[100:101], v[100:101], v[126:127]
	v_and_b32_e32 v127, 0xffff0000, v138
	v_mul_f32_e32 v163, v77, v96
	v_and_b32_e32 v96, 0xffff0000, v141
	v_pk_add_f32 v[142:143], v[106:107], v[164:165]
	v_lshlrev_b32_e32 v165, 16, v140
	v_lshlrev_b32_e32 v164, 16, v139
	v_and_b32_e32 v138, 0xffff0000, v139
	v_lshlrev_b32_e32 v139, 16, v141
	v_pk_mov_b32 v[140:141], v[66:67], v[78:79] op_sel:[1,0]
	v_pk_fma_f32 v[110:111], v[110:111], s[24:25], v[144:145] op_sel_hi:[1,0,1]
	v_pk_mul_f32 v[138:139], v[140:141], v[138:139]
	v_pk_add_f32 v[140:141], v[106:107], v[142:143] op_sel:[1,0] op_sel_hi:[0,1]
	v_pk_add_f32 v[144:145], v[108:109], v[108:109] op_sel:[0,1] op_sel_hi:[1,0]
	s_waitcnt lgkmcnt(0)
	v_mov_b32_e32 v98, v140
	v_pk_add_f32 v[144:145], v[110:111], v[144:145]
	v_pk_add_f32 v[140:141], v[140:141], s[20:21]
	v_pk_mul_f32 v[98:99], v[98:99], s[2:3]
	v_mov_b32_e32 v149, v65
	v_mul_f32_e32 v96, v79, v96
	v_mov_b32_e32 v141, v99
	v_pk_add_f32 v[98:99], v[110:111], v[144:145] op_sel:[1,0] op_sel_hi:[0,1]
	v_pk_mul_f32 v[148:149], v[148:149], v[126:127]
	v_mov_b32_e32 v99, v96
	v_pk_add_f32 v[98:99], v[140:141], v[98:99]
	v_mov_b32_e32 v140, v100
	v_mov_b32_e32 v141, v148
	v_mov_b32_e32 v148, v101
	v_mov_b32_e32 v166, v66
	v_mov_b32_e32 v167, v76
	v_pk_add_f32 v[100:101], v[140:141], v[148:149]
	v_mul_f32_e32 v97, 0x3fb504f3, v97
	v_pk_mul_f32 v[164:165], v[166:167], v[164:165]
	v_mov_b32_e32 v96, v100
	v_mov_b32_e32 v162, v101
	v_pk_fma_f32 v[102:103], v[102:103], s[24:25], v[164:165] op_sel_hi:[1,0,1]
	v_pk_add_f32 v[96:97], v[96:97], v[162:163]
	v_pk_fma_f32 v[138:139], v[146:147], s[24:25], v[138:139] op_sel_hi:[1,0,1]
	v_pk_add_f32 v[140:141], v[102:103], v[96:97]
	v_mov_b32_e32 v164, v102
	v_pk_add_f32 v[140:141], v[138:139], v[140:141]
	v_mov_b32_e32 v165, v138
	v_pk_add_f32 v[140:141], v[98:99], v[140:141]
	v_ashrrev_i32_e32 v115, 31, v114
	v_add_f32_e32 v96, v140, v141
	ds_bpermute_b32 v98, v150, v96
	s_waitcnt lgkmcnt(0)
	v_add_f32_e32 v96, v96, v98
	ds_bpermute_b32 v98, v151, v96
	s_waitcnt lgkmcnt(0)
	v_add_f32_e32 v96, v96, v98
	ds_bpermute_b32 v98, v152, v96
	s_waitcnt lgkmcnt(0)
	v_add_f32_e32 v96, v96, v98
	ds_bpermute_b32 v98, v153, v96
	s_waitcnt lgkmcnt(0)
	v_add_f32_e32 v96, v96, v98
	ds_bpermute_b32 v98, v154, v96
	s_waitcnt lgkmcnt(0)
	v_add_f32_e32 v96, v96, v98
	ds_bpermute_b32 v98, v155, v96
	s_waitcnt lgkmcnt(0)
	v_add_f32_e32 v96, v96, v98
	v_mul_f32_e32 v140, 0x3a800000, v96
	v_pk_add_f32 v[104:105], v[104:105], v[140:141] op_sel_hi:[1,0] neg_lo:[0,1] neg_hi:[0,1]
	v_pk_add_f32 v[106:107], v[106:107], v[140:141] op_sel_hi:[1,0] neg_lo:[0,1] neg_hi:[0,1]
	v_pk_mul_f32 v[142:143], v[104:105], v[104:105]
	v_pk_mul_f32 v[144:145], v[106:107], v[106:107]
	v_add_f32_e32 v102, v142, v143
	v_pk_add_f32 v[108:109], v[108:109], v[140:141] op_sel_hi:[1,0] neg_lo:[0,1] neg_hi:[0,1]
	v_add_f32_e32 v102, v144, v102
	v_pk_mul_f32 v[148:149], v[108:109], v[108:109]
	v_add_f32_e32 v102, v145, v102
	v_pk_add_f32 v[110:111], v[110:111], v[140:141] op_sel_hi:[1,0] neg_lo:[0,1] neg_hi:[0,1]
	v_add_f32_e32 v102, v148, v102
	v_pk_mul_f32 v[162:163], v[110:111], v[110:111]
	v_add_f32_e32 v102, v149, v102
	v_pk_add_f32 v[146:147], v[100:101], v[140:141] op_sel_hi:[1,0] neg_lo:[0,1] neg_hi:[0,1]
	v_add_f32_e32 v102, v162, v102
	v_pk_mul_f32 v[100:101], v[146:147], v[146:147]
	v_add_f32_e32 v102, v163, v102
	v_pk_add_f32 v[164:165], v[164:165], v[140:141] op_sel_hi:[1,0] neg_lo:[0,1] neg_hi:[0,1]
	v_add_f32_e32 v100, v100, v102
	v_pk_mul_f32 v[166:167], v[164:165], v[164:165]
	v_mov_b32_e32 v96, v103
	v_add_f32_e32 v100, v101, v100
	v_pk_add_f32 v[168:169], v[96:97], v[140:141] op_sel_hi:[1,0] neg_lo:[0,1] neg_hi:[0,1]
	v_add_f32_e32 v100, v166, v100
	v_pk_mul_f32 v[96:97], v[168:169], v[168:169]
	v_mov_b32_e32 v98, v139
	v_add_f32_e32 v100, v167, v100
	v_pk_add_f32 v[138:139], v[98:99], v[140:141] op_sel_hi:[1,0] neg_lo:[0,1] neg_hi:[0,1]
	v_add_f32_e32 v96, v96, v100
	v_pk_mul_f32 v[98:99], v[138:139], v[138:139]
	v_add_f32_e32 v96, v97, v96
	v_add_f32_e32 v96, v98, v96
	v_add_f32_e32 v96, v99, v96
	ds_bpermute_b32 v97, v150, v96
	v_pk_add_f32 v[102:103], v[34:35], 1.0 op_sel_hi:[1,0]
	v_pk_add_f32 v[144:145], v[40:41], 1.0 op_sel_hi:[1,0]
	v_pk_add_f32 v[148:149], v[42:43], 1.0 op_sel_hi:[1,0]
	v_pk_add_f32 v[162:163], v[56:57], 1.0 op_sel_hi:[1,0]
	s_waitcnt lgkmcnt(0)
	v_add_f32_e32 v96, v96, v97
	ds_bpermute_b32 v97, v151, v96
	v_pk_add_f32 v[166:167], v[58:59], 1.0 op_sel_hi:[1,0]
	s_waitcnt lgkmcnt(0)
	v_add_f32_e32 v96, v96, v97
	ds_bpermute_b32 v97, v152, v96
	s_waitcnt lgkmcnt(0)
	v_add_f32_e32 v96, v96, v97
	ds_bpermute_b32 v97, v153, v96
	s_waitcnt lgkmcnt(0)
	v_add_f32_e32 v98, v96, v97
	ds_bpermute_b32 v99, v154, v98
	v_lshlrev_b64 v[96:97], 12, v[114:115]
	v_lshl_add_u64 v[140:141], v[122:123], 0, v[96:97]
	v_pk_add_f32 v[96:97], v[32:33], 1.0 op_sel_hi:[1,0]
	s_waitcnt lgkmcnt(0)
	v_add_f32_e32 v100, v98, v99
	ds_bpermute_b32 v101, v155, v100
	v_lshlrev_b64 v[98:99], 11, v[114:115]
	v_lshl_add_u64 v[142:143], v[124:125], 0, v[98:99]
	s_waitcnt lgkmcnt(0)
	v_add_f32_e32 v98, v100, v101
	v_fmamk_f32 v98, v98, 0x3a800000, v159
	v_mul_f32_e32 v99, 0x4b800000, v98
	v_cmp_gt_f32_e32 vcc, s21, v98
	s_nop 1
	v_cndmask_b32_e32 v98, v98, v99, vcc
	v_rsq_f32_e32 v98, v98
	s_nop 0
	v_mul_f32_e32 v99, 0x45800000, v98
	v_cndmask_b32_e32 v170, v98, v99, vcc
	v_pk_mul_f32 v[98:99], v[104:105], v[170:171] op_sel_hi:[1,0]
	v_pk_mul_f32 v[100:101], v[106:107], v[170:171] op_sel_hi:[1,0]
	v_pk_fma_f32 v[98:99], v[28:29], v[98:99], v[24:25]
	v_pk_fma_f32 v[100:101], v[30:31], v[100:101], v[26:27]
	global_store_dwordx4 v[140:141], v[98:101], off sc1 nt
	s_nop 1
	v_pk_fma_f32 v[98:99], v[96:97], v[98:99], v[44:45]
	v_pk_fma_f32 v[96:97], v[102:103], v[100:101], v[46:47]
	v_cvt_pk_bf16_f32 v100, v98, v99
	v_cvt_pk_bf16_f32 v101, v96, v97
	global_store_dwordx2 v[142:143], v[100:101], off
	v_pk_mul_f32 v[100:101], v[108:109], v[170:171] op_sel_hi:[1,0]
	s_nop 0
	v_pk_fma_f32 v[102:103], v[20:21], v[100:101], v[12:13]
	v_pk_mul_f32 v[100:101], v[110:111], v[170:171] op_sel_hi:[1,0]
	v_pk_mul_f32 v[110:111], v[138:139], v[170:171] op_sel_hi:[1,0]
	v_pk_fma_f32 v[104:105], v[22:23], v[100:101], v[14:15]
	global_store_dwordx4 v[140:141], v[102:105], off offset:1024 sc1 nt
	v_pk_fma_f32 v[100:101], v[148:149], v[104:105], v[50:51]
	v_pk_fma_f32 v[110:111], v[6:7], v[110:111], v[2:3]
	v_pk_fma_f32 v[102:103], v[144:145], v[102:103], v[48:49]
	v_cvt_pk_bf16_f32 v105, v100, v101
	v_cvt_pk_bf16_f32 v104, v102, v103
	global_store_dwordx2 v[142:143], v[104:105], off offset:512
	v_pk_mul_f32 v[104:105], v[146:147], v[170:171] op_sel_hi:[1,0]
	v_pk_add_f32 v[138:139], v[68:69], 1.0 op_sel_hi:[1,0]
	v_pk_fma_f32 v[106:107], v[16:17], v[104:105], v[8:9]
	v_pk_mul_f32 v[104:105], v[164:165], v[170:171] op_sel_hi:[1,0]
	s_nop 0
	v_pk_fma_f32 v[108:109], v[18:19], v[104:105], v[10:11]
	global_store_dwordx4 v[140:141], v[106:109], off offset:2048 sc1 nt
	v_pk_fma_f32 v[104:105], v[166:167], v[108:109], v[62:63]
	s_nop 0
	v_pk_fma_f32 v[106:107], v[162:163], v[106:107], v[60:61]
	v_cvt_pk_bf16_f32 v109, v104, v105
	v_cvt_pk_bf16_f32 v108, v106, v107
	global_store_dwordx2 v[142:143], v[108:109], off offset:1024
	v_pk_mul_f32 v[108:109], v[168:169], v[170:171] op_sel_hi:[1,0]
	s_nop 0
	v_pk_fma_f32 v[108:109], v[4:5], v[108:109], v[0:1]
	global_store_dwordx4 v[140:141], v[108:111], off offset:3072 sc1 nt
	s_nop 1
	v_pk_fma_f32 v[108:109], v[138:139], v[108:109], v[72:73]
	v_pk_add_f32 v[138:139], v[70:71], 1.0 op_sel_hi:[1,0]
	v_cvt_pk_bf16_f32 v144, v108, v109
	v_pk_fma_f32 v[110:111], v[138:139], v[110:111], v[74:75]
	v_cvt_pk_bf16_f32 v145, v110, v111
	global_store_dwordx2 v[142:143], v[144:145], off offset:1536
	ds_read_b128 v[216:219], v156
	ds_read_b128 v[220:223], v156 offset:4096
	ds_read_b128 v[224:227], v156 offset:1024
	ds_read_b128 v[228:231], v156 offset:5120
	ds_read_b128 v[232:235], v156 offset:2048
	ds_read_b128 v[236:239], v156 offset:6144
	ds_read_b128 v[240:243], v156 offset:3072
	ds_read_b128 v[244:247], v156 offset:7168
	ds_read_b128 v[248:251], v156 offset:8192
	ds_read_b128 v[192:195], v156 offset:12288
	ds_read_b128 v[196:199], v156 offset:9216
	ds_read_b128 v[200:203], v156 offset:13312
	s_waitcnt lgkmcnt(10)
	v_pk_mul_f32 v[204:205], v[98:99], v[216:217]
	v_pk_mul_f32 v[206:207], v[98:99], v[220:221]
	v_pk_fma_f32 v[204:205], v[96:97], v[218:219], v[204:205]
	v_pk_fma_f32 v[206:207], v[96:97], v[222:223], v[206:207]
	ds_read_b128 v[216:219], v156 offset:10240
	ds_read_b128 v[220:223], v156 offset:14336
	s_waitcnt lgkmcnt(10)
	v_pk_fma_f32 v[204:205], v[102:103], v[224:225], v[204:205]
	v_pk_fma_f32 v[206:207], v[102:103], v[228:229], v[206:207]
	v_pk_fma_f32 v[204:205], v[100:101], v[226:227], v[204:205]
	v_pk_fma_f32 v[206:207], v[100:101], v[230:231], v[206:207]
	ds_read_b128 v[224:227], v156 offset:11264
	ds_read_b128 v[228:231], v156 offset:15360
	s_waitcnt lgkmcnt(10)
	v_pk_fma_f32 v[204:205], v[106:107], v[232:233], v[204:205]
	v_pk_fma_f32 v[206:207], v[106:107], v[236:237], v[206:207]
	v_pk_fma_f32 v[204:205], v[104:105], v[234:235], v[204:205]
	v_pk_fma_f32 v[206:207], v[104:105], v[238:239], v[206:207]
	ds_read_b128 v[232:235], v156 offset:16384
	ds_read_b128 v[236:239], v156 offset:20480
	s_waitcnt lgkmcnt(10)
	v_pk_fma_f32 v[204:205], v[108:109], v[240:241], v[204:205]
	v_pk_fma_f32 v[206:207], v[108:109], v[244:245], v[206:207]
	v_pk_fma_f32 v[204:205], v[110:111], v[242:243], v[204:205]
	v_pk_fma_f32 v[206:207], v[110:111], v[246:247], v[206:207]
	ds_read_b128 v[240:243], v156 offset:17408
	ds_read_b128 v[244:247], v156 offset:21504
	v_add_f32_e32 v115, v204, v205
	v_add_f32_e32 v127, v206, v207
	s_waitcnt lgkmcnt(10)
	v_pk_mul_f32 v[208:209], v[98:99], v[248:249]
	v_pk_mul_f32 v[210:211], v[98:99], v[192:193]
	v_pk_fma_f32 v[208:209], v[96:97], v[250:251], v[208:209]
	v_pk_fma_f32 v[210:211], v[96:97], v[194:195], v[210:211]
	ds_read_b128 v[248:251], v156 offset:18432
	ds_read_b128 v[192:195], v156 offset:22528
	s_waitcnt lgkmcnt(10)
	v_pk_fma_f32 v[208:209], v[102:103], v[196:197], v[208:209]
	v_pk_fma_f32 v[210:211], v[102:103], v[200:201], v[210:211]
	v_pk_fma_f32 v[208:209], v[100:101], v[198:199], v[208:209]
	v_pk_fma_f32 v[210:211], v[100:101], v[202:203], v[210:211]
	ds_read_b128 v[196:199], v156 offset:19456
	ds_read_b128 v[200:203], v156 offset:23552
	s_waitcnt lgkmcnt(10)
	v_pk_fma_f32 v[208:209], v[106:107], v[216:217], v[208:209]
	v_pk_fma_f32 v[210:211], v[106:107], v[220:221], v[210:211]
	v_pk_fma_f32 v[208:209], v[104:105], v[218:219], v[208:209]
	v_pk_fma_f32 v[210:211], v[104:105], v[222:223], v[210:211]
	ds_read_b128 v[216:219], v156 offset:24576
	ds_read_b128 v[220:223], v156 offset:28672
	s_waitcnt lgkmcnt(10)
	v_pk_fma_f32 v[208:209], v[108:109], v[224:225], v[208:209]
	v_pk_fma_f32 v[210:211], v[108:109], v[228:229], v[210:211]
	v_pk_fma_f32 v[208:209], v[110:111], v[226:227], v[208:209]
	v_pk_fma_f32 v[210:211], v[110:111], v[230:231], v[210:211]
	ds_read_b128 v[224:227], v156 offset:25600
	ds_read_b128 v[228:231], v156 offset:29696
	v_add_f32_e32 v129, v208, v209
	v_add_f32_e32 v138, v210, v211
	s_waitcnt lgkmcnt(10)
	v_pk_mul_f32 v[204:205], v[98:99], v[232:233]
	v_pk_mul_f32 v[206:207], v[98:99], v[236:237]
	v_pk_fma_f32 v[204:205], v[96:97], v[234:235], v[204:205]
	v_pk_fma_f32 v[206:207], v[96:97], v[238:239], v[206:207]
	ds_read_b128 v[232:235], v156 offset:26624
	ds_read_b128 v[236:239], v156 offset:30720
	s_waitcnt lgkmcnt(10)
	v_pk_fma_f32 v[204:205], v[102:103], v[240:241], v[204:205]
	v_pk_fma_f32 v[206:207], v[102:103], v[244:245], v[206:207]
	v_pk_fma_f32 v[204:205], v[100:101], v[242:243], v[204:205]
	v_pk_fma_f32 v[206:207], v[100:101], v[246:247], v[206:207]
	ds_read_b128 v[240:243], v156 offset:27648
	ds_read_b128 v[244:247], v156 offset:31744
	s_waitcnt lgkmcnt(10)
	v_pk_fma_f32 v[204:205], v[106:107], v[248:249], v[204:205]
	v_pk_fma_f32 v[206:207], v[106:107], v[192:193], v[206:207]
	v_pk_fma_f32 v[204:205], v[104:105], v[250:251], v[204:205]
	v_pk_fma_f32 v[206:207], v[104:105], v[194:195], v[206:207]
	ds_read_b128 v[248:251], v156 offset:32768
	ds_read_b128 v[192:195], v156 offset:36864
	s_waitcnt lgkmcnt(10)
	v_pk_fma_f32 v[204:205], v[108:109], v[196:197], v[204:205]
	v_pk_fma_f32 v[206:207], v[108:109], v[200:201], v[206:207]
	v_pk_fma_f32 v[204:205], v[110:111], v[198:199], v[204:205]
	v_pk_fma_f32 v[206:207], v[110:111], v[202:203], v[206:207]
	ds_read_b128 v[196:199], v156 offset:33792
	ds_read_b128 v[200:203], v156 offset:37888
	v_add_f32_e32 v139, v204, v205
	v_add_f32_e32 v148, v206, v207
	s_waitcnt lgkmcnt(10)
	v_pk_mul_f32 v[208:209], v[98:99], v[216:217]
	v_pk_mul_f32 v[210:211], v[98:99], v[220:221]
	v_pk_fma_f32 v[208:209], v[96:97], v[218:219], v[208:209]
	v_pk_fma_f32 v[210:211], v[96:97], v[222:223], v[210:211]
	ds_read_b128 v[216:219], v156 offset:34816
	ds_read_b128 v[220:223], v156 offset:38912
	s_waitcnt lgkmcnt(10)
	v_pk_fma_f32 v[208:209], v[102:103], v[224:225], v[208:209]
	v_pk_fma_f32 v[210:211], v[102:103], v[228:229], v[210:211]
	v_pk_fma_f32 v[208:209], v[100:101], v[226:227], v[208:209]
	v_pk_fma_f32 v[210:211], v[100:101], v[230:231], v[210:211]
	ds_read_b128 v[224:227], v156 offset:35840
	ds_read_b128 v[228:231], v156 offset:39936
	s_waitcnt lgkmcnt(10)
	v_pk_fma_f32 v[208:209], v[106:107], v[232:233], v[208:209]
	v_pk_fma_f32 v[210:211], v[106:107], v[236:237], v[210:211]
	v_pk_fma_f32 v[208:209], v[104:105], v[234:235], v[208:209]
	v_pk_fma_f32 v[210:211], v[104:105], v[238:239], v[210:211]
	ds_read_b128 v[232:235], v156 offset:40960
	ds_read_b128 v[236:239], v156 offset:45056
	s_waitcnt lgkmcnt(10)
	v_pk_fma_f32 v[208:209], v[108:109], v[240:241], v[208:209]
	v_pk_fma_f32 v[210:211], v[108:109], v[244:245], v[210:211]
	v_pk_fma_f32 v[208:209], v[110:111], v[242:243], v[208:209]
	v_pk_fma_f32 v[210:211], v[110:111], v[246:247], v[210:211]
	ds_read_b128 v[240:243], v156 offset:41984
	ds_read_b128 v[244:247], v156 offset:46080
	v_add_f32_e32 v149, v208, v209
	v_add_f32_e32 v161, v210, v211
	s_waitcnt lgkmcnt(10)
	v_pk_mul_f32 v[204:205], v[98:99], v[248:249]
	v_pk_mul_f32 v[206:207], v[98:99], v[192:193]
	v_pk_fma_f32 v[204:205], v[96:97], v[250:251], v[204:205]
	v_pk_fma_f32 v[206:207], v[96:97], v[194:195], v[206:207]
	ds_read_b128 v[248:251], v156 offset:43008
	ds_read_b128 v[192:195], v156 offset:47104
	s_waitcnt lgkmcnt(10)
	v_pk_fma_f32 v[204:205], v[102:103], v[196:197], v[204:205]
	v_pk_fma_f32 v[206:207], v[102:103], v[200:201], v[206:207]
	v_pk_fma_f32 v[204:205], v[100:101], v[198:199], v[204:205]
	v_pk_fma_f32 v[206:207], v[100:101], v[202:203], v[206:207]
	ds_read_b128 v[196:199], v156 offset:44032
	ds_read_b128 v[200:203], v156 offset:48128
	s_waitcnt lgkmcnt(10)
	v_pk_fma_f32 v[204:205], v[106:107], v[216:217], v[204:205]
	v_pk_fma_f32 v[206:207], v[106:107], v[220:221], v[206:207]
	v_pk_fma_f32 v[204:205], v[104:105], v[218:219], v[204:205]
	v_pk_fma_f32 v[206:207], v[104:105], v[222:223], v[206:207]
	ds_read_b128 v[216:219], v156 offset:49152
	ds_read_b128 v[220:223], v156 offset:53248
	s_waitcnt lgkmcnt(10)
	v_pk_fma_f32 v[204:205], v[108:109], v[224:225], v[204:205]
	v_pk_fma_f32 v[206:207], v[108:109], v[228:229], v[206:207]
	v_pk_fma_f32 v[204:205], v[110:111], v[226:227], v[204:205]
	v_pk_fma_f32 v[206:207], v[110:111], v[230:231], v[206:207]
	ds_read_b128 v[224:227], v156 offset:50176
	ds_read_b128 v[228:231], v156 offset:54272
	v_add_f32_e32 v170, v204, v205
	v_add_f32_e32 v171, v206, v207
	s_waitcnt lgkmcnt(10)
	v_pk_mul_f32 v[208:209], v[98:99], v[232:233]
	v_pk_mul_f32 v[210:211], v[98:99], v[236:237]
	v_pk_fma_f32 v[208:209], v[96:97], v[234:235], v[208:209]
	v_pk_fma_f32 v[210:211], v[96:97], v[238:239], v[210:211]
	ds_read_b128 v[232:235], v156 offset:51200
	ds_read_b128 v[236:239], v156 offset:55296
	s_waitcnt lgkmcnt(10)
	v_pk_fma_f32 v[208:209], v[102:103], v[240:241], v[208:209]
	v_pk_fma_f32 v[210:211], v[102:103], v[244:245], v[210:211]
	v_pk_fma_f32 v[208:209], v[100:101], v[242:243], v[208:209]
	v_pk_fma_f32 v[210:211], v[100:101], v[246:247], v[210:211]
	ds_read_b128 v[240:243], v156 offset:52224
	ds_read_b128 v[244:247], v156 offset:56320
	s_waitcnt lgkmcnt(10)
	v_pk_fma_f32 v[208:209], v[106:107], v[248:249], v[208:209]
	v_pk_fma_f32 v[210:211], v[106:107], v[192:193], v[210:211]
	v_pk_fma_f32 v[208:209], v[104:105], v[250:251], v[208:209]
	v_pk_fma_f32 v[210:211], v[104:105], v[194:195], v[210:211]
	ds_read_b128 v[248:251], v156 offset:57344
	ds_read_b128 v[192:195], v156 offset:61440
	s_waitcnt lgkmcnt(10)
	v_pk_fma_f32 v[208:209], v[108:109], v[196:197], v[208:209]
	v_pk_fma_f32 v[210:211], v[108:109], v[200:201], v[210:211]
	v_pk_fma_f32 v[208:209], v[110:111], v[198:199], v[208:209]
	v_pk_fma_f32 v[210:211], v[110:111], v[202:203], v[210:211]
	ds_read_b128 v[196:199], v156 offset:58368
	ds_read_b128 v[200:203], v156 offset:62464
	v_add_f32_e32 v172, v208, v209
	v_add_f32_e32 v173, v210, v211
	s_waitcnt lgkmcnt(10)
	v_pk_mul_f32 v[204:205], v[98:99], v[216:217]
	v_pk_mul_f32 v[206:207], v[98:99], v[220:221]
	v_pk_fma_f32 v[204:205], v[96:97], v[218:219], v[204:205]
	v_pk_fma_f32 v[206:207], v[96:97], v[222:223], v[206:207]
	ds_read_b128 v[216:219], v156 offset:59392
	ds_read_b128 v[220:223], v156 offset:63488
	s_waitcnt lgkmcnt(10)
	v_pk_fma_f32 v[204:205], v[102:103], v[224:225], v[204:205]
	v_pk_fma_f32 v[206:207], v[102:103], v[228:229], v[206:207]
	v_pk_fma_f32 v[204:205], v[100:101], v[226:227], v[204:205]
	v_pk_fma_f32 v[206:207], v[100:101], v[230:231], v[206:207]
	ds_read_b128 v[224:227], v156 offset:60416
	ds_read_b128 v[228:231], v156 offset:64512
	s_waitcnt lgkmcnt(10)
	v_pk_fma_f32 v[204:205], v[106:107], v[232:233], v[204:205]
	v_pk_fma_f32 v[206:207], v[106:107], v[236:237], v[206:207]
	v_pk_fma_f32 v[204:205], v[104:105], v[234:235], v[204:205]
	v_pk_fma_f32 v[206:207], v[104:105], v[238:239], v[206:207]
	s_waitcnt lgkmcnt(8)
	v_pk_fma_f32 v[204:205], v[108:109], v[240:241], v[204:205]
	v_pk_fma_f32 v[206:207], v[108:109], v[244:245], v[206:207]
	v_pk_fma_f32 v[204:205], v[110:111], v[242:243], v[204:205]
	v_pk_fma_f32 v[206:207], v[110:111], v[246:247], v[206:207]
	v_add_f32_e32 v174, v204, v205
	v_add_f32_e32 v175, v206, v207
	s_waitcnt lgkmcnt(6)
	v_pk_mul_f32 v[208:209], v[98:99], v[248:249]
	v_pk_mul_f32 v[210:211], v[98:99], v[192:193]
	v_pk_fma_f32 v[208:209], v[96:97], v[250:251], v[208:209]
	v_pk_fma_f32 v[210:211], v[96:97], v[194:195], v[210:211]
	s_waitcnt lgkmcnt(4)
	v_pk_fma_f32 v[208:209], v[102:103], v[196:197], v[208:209]
	v_pk_fma_f32 v[210:211], v[102:103], v[200:201], v[210:211]
	v_pk_fma_f32 v[208:209], v[100:101], v[198:199], v[208:209]
	v_pk_fma_f32 v[210:211], v[100:101], v[202:203], v[210:211]
	s_waitcnt lgkmcnt(2)
	v_pk_fma_f32 v[208:209], v[106:107], v[216:217], v[208:209]
	v_pk_fma_f32 v[210:211], v[106:107], v[220:221], v[210:211]
	v_pk_fma_f32 v[208:209], v[104:105], v[218:219], v[208:209]
	v_pk_fma_f32 v[210:211], v[104:105], v[222:223], v[210:211]
	s_waitcnt lgkmcnt(0)
	v_pk_fma_f32 v[208:209], v[108:109], v[224:225], v[208:209]
	v_pk_fma_f32 v[210:211], v[108:109], v[228:229], v[210:211]
	v_pk_fma_f32 v[208:209], v[110:111], v[226:227], v[208:209]
	v_pk_fma_f32 v[210:211], v[110:111], v[230:231], v[210:211]
	v_add_f32_e32 v176, v208, v209
	v_add_f32_e32 v96, v210, v211
	v_cndmask_b32_e64 v97, v115, v170, s[6:7]
	ds_bpermute_b32 v97, v150, v97
	v_cndmask_b32_e64 v99, v127, v171, s[6:7]
	ds_bpermute_b32 v99, v150, v99
	v_cndmask_b32_e64 v100, v129, v172, s[6:7]
	ds_bpermute_b32 v100, v150, v100
	v_cndmask_b32_e64 v98, v170, v115, s[6:7]
	s_waitcnt lgkmcnt(2)
	v_add_f32_e32 v97, v98, v97
	v_cndmask_b32_e64 v98, v171, v127, s[6:7]
	s_waitcnt lgkmcnt(1)
	v_add_f32_e32 v98, v98, v99
	v_cndmask_b32_e64 v99, v172, v129, s[6:7]
	s_waitcnt lgkmcnt(0)
	v_add_f32_e32 v99, v99, v100
	v_cndmask_b32_e64 v100, v138, v173, s[6:7]
	ds_bpermute_b32 v100, v150, v100
	v_cndmask_b32_e64 v102, v139, v174, s[6:7]
	ds_bpermute_b32 v102, v150, v102
	v_cndmask_b32_e64 v103, v148, v175, s[6:7]
	ds_bpermute_b32 v103, v150, v103
	v_cndmask_b32_e64 v101, v173, v138, s[6:7]
	s_waitcnt lgkmcnt(2)
	v_add_f32_e32 v100, v101, v100
	v_cndmask_b32_e64 v101, v174, v139, s[6:7]
	s_waitcnt lgkmcnt(1)
	v_add_f32_e32 v101, v101, v102
	v_cndmask_b32_e64 v102, v175, v148, s[6:7]
	s_waitcnt lgkmcnt(0)
	v_add_f32_e32 v102, v102, v103
	v_cndmask_b32_e64 v103, v149, v176, s[6:7]
	v_cndmask_b32_e64 v105, v161, v96, s[6:7]
	ds_bpermute_b32 v103, v150, v103
	ds_bpermute_b32 v105, v150, v105
	v_cndmask_b32_e64 v104, v176, v149, s[6:7]
	v_cndmask_b32_e64 v96, v96, v161, s[6:7]
	v_cndmask_b32_e64 v106, v97, v101, s[8:9]
	s_waitcnt lgkmcnt(1)
	v_add_f32_e32 v103, v104, v103
	s_waitcnt lgkmcnt(0)
	v_add_f32_e32 v96, v96, v105
	v_cndmask_b32_e64 v97, v101, v97, s[8:9]
	v_cndmask_b32_e64 v101, v98, v102, s[8:9]
	v_cndmask_b32_e64 v98, v102, v98, s[8:9]
	v_cndmask_b32_e64 v102, v99, v103, s[8:9]
	v_cndmask_b32_e64 v104, v100, v96, s[8:9]
	ds_bpermute_b32 v106, v151, v106
	ds_bpermute_b32 v101, v151, v101
	ds_bpermute_b32 v102, v151, v102
	ds_bpermute_b32 v104, v151, v104
	v_cndmask_b32_e64 v99, v103, v99, s[8:9]
	v_cndmask_b32_e64 v96, v96, v100, s[8:9]
	s_waitcnt lgkmcnt(3)
	v_add_f32_e32 v97, v97, v106
	s_waitcnt lgkmcnt(2)
	v_add_f32_e32 v98, v98, v101
	s_waitcnt lgkmcnt(1)
	v_add_f32_e32 v99, v99, v102
	s_waitcnt lgkmcnt(0)
	v_add_f32_e32 v96, v96, v104
	v_cndmask_b32_e64 v100, v97, v99, s[10:11]
	v_cndmask_b32_e64 v101, v98, v96, s[10:11]
	ds_bpermute_b32 v100, v152, v100
	ds_bpermute_b32 v101, v152, v101
	v_cndmask_b32_e64 v97, v99, v97, s[10:11]
	v_cndmask_b32_e64 v96, v96, v98, s[10:11]
	s_waitcnt lgkmcnt(1)
	v_add_f32_e32 v97, v97, v100
	s_waitcnt lgkmcnt(0)
	v_add_f32_e32 v96, v96, v101
	v_cndmask_b32_e64 v98, v97, v96, s[12:13]
	ds_bpermute_b32 v98, v153, v98
	v_cndmask_b32_e64 v96, v96, v97, s[12:13]
	s_waitcnt lgkmcnt(0)
	v_add_f32_e32 v96, v96, v98
	ds_bpermute_b32 v97, v154, v96
	s_waitcnt lgkmcnt(0)
	v_add_f32_e32 v96, v96, v97
	ds_bpermute_b32 v97, v155, v96
	s_waitcnt lgkmcnt(0)
	v_add_f32_e32 v96, v96, v97
	ds_bpermute_b32 v97, v153, v96
	s_waitcnt lgkmcnt(0)
	v_max_f32_e32 v97, v97, v97
	v_max_f32_e32 v97, v96, v97
	ds_bpermute_b32 v98, v152, v97
	s_waitcnt lgkmcnt(0)
	v_max_f32_e32 v98, v98, v98
	v_max_f32_e32 v97, v97, v98
	ds_bpermute_b32 v98, v151, v97
	s_waitcnt lgkmcnt(0)
	v_max_f32_e32 v98, v98, v98
	v_max_f32_e32 v97, v97, v98
	ds_bpermute_b32 v98, v150, v97
	s_waitcnt lgkmcnt(0)
	v_max_f32_e32 v98, v98, v98
	v_max_f32_e32 v97, v97, v98
	v_sub_f32_e32 v96, v96, v97
	v_mul_f32_e32 v97, 0x3fb8aa3b, v96
	v_fma_f32 v98, v96, s25, -v97
	v_rndne_f32_e32 v99, v97
	v_fmac_f32_e32 v98, 0x32a5705f, v96
	v_sub_f32_e32 v97, v97, v99
	v_add_f32_e32 v97, v97, v98
	v_exp_f32_e32 v97, v97
	v_cvt_i32_f32_e32 v98, v99
	v_cmp_ngt_f32_e32 vcc, s28, v96
	v_ldexp_f32 v97, v97, v98
	s_nop 0
	v_cndmask_b32_e32 v97, 0, v97, vcc
	v_cmp_nlt_f32_e32 vcc, s29, v96
	s_nop 1
	v_cndmask_b32_e32 v96, v160, v97, vcc
	ds_bpermute_b32 v97, v153, v96
	s_waitcnt lgkmcnt(0)
	v_add_f32_e32 v97, v96, v97
	ds_bpermute_b32 v98, v152, v97
	s_waitcnt lgkmcnt(0)
	v_add_f32_e32 v97, v97, v98
	ds_bpermute_b32 v98, v151, v97
	s_waitcnt lgkmcnt(0)
	v_add_f32_e32 v97, v97, v98
	ds_bpermute_b32 v98, v150, v97
	s_and_saveexec_b64 s[26:27], s[14:15]
	s_cbranch_execz .LBB0_1394
	s_waitcnt lgkmcnt(0)
	v_add_f32_e32 v97, v97, v98
	v_div_scale_f32 v98, s[30:31], v97, v97, v96
	v_rcp_f32_e32 v99, v98
	v_and_b32_e32 v100, 0xfff, v114
	v_fma_f32 v101, -v98, v99, 1.0
	v_fmac_f32_e32 v99, v101, v99
	v_div_scale_f32 v101, vcc, v96, v97, v96
	v_mul_f32_e32 v102, v101, v99
	v_fma_f32 v103, -v98, v102, v101
	v_fmac_f32_e32 v102, v103, v99
	v_fma_f32 v98, -v98, v102, v101
	v_div_fmas_f32 v98, v98, v99, v102
	v_div_fixup_f32 v98, v98, v97, v96
	v_lshl_or_b32 v96, v112, 4, v157
	v_ashrrev_i32_e32 v97, 31, v96
	v_lshlrev_b64 v[96:97], 14, v[96:97]
	v_lshl_add_u64 v[96:97], s[18:19], 0, v[96:97]
	v_lshlrev_b32_e32 v112, 2, v100
	v_lshl_add_u64 v[96:97], v[96:97], 0, v[112:113]
	global_store_dword v[96:97], v98, off
	s_branch .LBB0_1394
